# attn_combine split in whole 2048-item trips: scan blocks 1 trip, other blocks 5 (no clamped duplicate lanes)
# speedup vs baseline: 1.0099x; 1.0019x over previous
; #define LAS __attribute__((address_space(3)))
; __device__ __forceinline__ unsigned pk2(float lo, float hi) { f32x2_t v = {lo, hi}; bf16x2_t b = __builtin_convertvector(v, bf16x2_t); return __builtin_bit_cast(unsigned, b); }
; __device__ __forceinline__ void attn_phase(LAS unsigned char* lds, const bf16* __restrict__ Q, const bf16* __restrict__ Kb, const bf16* __restrict__ Vb, unsigned char* ws, float* PM, int tid, int wave, int lane) {
;     ...
;         float l = 0.f; u32x4 pw[5][2];
; #pragma unroll
;         for (int i = 0; i < 5; ++i) {
; #pragma unroll
;             for (int e = 0; e < 16; ++e) { sacc[i][e] = __builtin_amdgcn_exp2f(sacc[i][e] - m); l += sacc[i][e]; }
; #pragma unroll
;             for (int s2 = 0; s2 < 2; ++s2) { pw[i][s2].x = pk2(sacc[i][8 * s2], sacc[i][8 * s2 + 1]); pw[i][s2].y = pk2(sacc[i][8 * s2 + 2], sacc[i][8 * s2 + 3]); pw[i][s2].z = pk2(sacc[i][8 * s2 + 4], sacc[i][8 * s2 + 5]); pw[i][s2].w = pk2(sacc[i][8 * s2 + 6], sacc[i][8 * s2 + 7]); }
;         }
;         { auto rr = __builtin_amdgcn_permlane32_swap(__float_as_uint(l), __float_as_uint(l), false, false); l = __uint_as_float(rr[0]) + __uint_as_float(rr[1]); }
;         LBAR();
;         ATT_STAGE_WRITE(VROW);
;         LBAR();
;         const AttnItem C = I;
;         const int nxt = it + (int)gridDim.x; const bool more = nxt < 1536;
;         if (more) { I = attn_decode(nxt); ATT_STAGE_LOAD(Kb, I); ATT_QLOAD(I); }
;         f32x16 oacc[4];
; #pragma unroll
;         for (int i = 0; i < 4; ++i)
; #pragma unroll
;             for (int e = 0; e < 16; ++e) oacc[i][e] = 0.f;
;         const LAS unsigned char* vbase = lds + (32 * wave + 4 * h + ((lane & 15) >> 2)) * VROW + (16 * ((lane >> 4) & 1) + 4 * (lane & 3)) * 2;
; #pragma unroll
;         for (int i = 0; i < 5; ++i)
; #pragma unroll
;             for (int s2 = 0; s2 < 2; ++s2)
; #pragma unroll
;                 for (int db = 0; db < 4; ++db) {
;                     const s16x4 lo = vtr(vbase + (32 * i + 16 * s2) * VROW + db * 64), hi = vtr(vbase + (32 * i + 16 * s2 + 8) * VROW + db * 64);
;                     const bf16x8 av = {lo[0], lo[1], lo[2], lo[3], hi[0], hi[1], hi[2], hi[3]};
;                     oacc[db] = __builtin_amdgcn_mfma_f32_32x32x16_bf16(av, __builtin_bit_cast(bf16x8, pw[i][s2]), oacc[db], 0, 0, 0);
;                 }
.LBB0_594:
	v_cvt_pk_bf16_f32 v0, v4, v5
	v_cvt_pk_bf16_f32 v1, v6, v7
	ds_read_b64_tr_b16 v[4:5], v211
	ds_read_b64_tr_b16 v[6:7], v211 offset:2560
	v_cvt_pk_bf16_f32 v2, v8, v9
	v_cvt_pk_bf16_f32 v3, v10, v11
	v_cvt_pk_bf16_f32 v166, v48, v49
	v_cvt_pk_bf16_f32 v167, v50, v51
	v_cvt_pk_bf16_f32 v76, v52, v53
	v_cvt_pk_bf16_f32 v77, v54, v55
	v_cvt_pk_bf16_f32 v78, v56, v57
	v_cvt_pk_bf16_f32 v79, v58, v59
	v_cvt_pk_bf16_f32 v72, v60, v61
	v_cvt_pk_bf16_f32 v73, v62, v63
	s_waitcnt lgkmcnt(0)
	v_mfma_f32_32x32x16_bf16 v[48:63], v[4:7], v[0:3], 0
	ds_read_b64_tr_b16 v[4:5], v211 offset:64
	ds_read_b64_tr_b16 v[6:7], v211 offset:2624
	v_cvt_pk_bf16_f32 v174, v32, v33
	v_cvt_pk_bf16_f32 v175, v34, v35
	v_cvt_pk_bf16_f32 v168, v36, v37
	v_cvt_pk_bf16_f32 v169, v38, v39
	v_cvt_pk_bf16_f32 v170, v40, v41
	v_cvt_pk_bf16_f32 v171, v42, v43
	v_cvt_pk_bf16_f32 v164, v44, v45
	v_cvt_pk_bf16_f32 v165, v46, v47
	s_waitcnt lgkmcnt(0)
	v_mfma_f32_32x32x16_bf16 v[32:47], v[4:7], v[0:3], 0
	ds_read_b64_tr_b16 v[4:5], v211 offset:128
	ds_read_b64_tr_b16 v[6:7], v211 offset:2688
	v_cvt_pk_bf16_f32 v182, v16, v17
	v_cvt_pk_bf16_f32 v183, v18, v19
	v_cvt_pk_bf16_f32 v176, v20, v21
	v_cvt_pk_bf16_f32 v177, v22, v23
	v_cvt_pk_bf16_f32 v178, v24, v25
	v_cvt_pk_bf16_f32 v179, v26, v27
	v_cvt_pk_bf16_f32 v172, v28, v29
	v_cvt_pk_bf16_f32 v173, v30, v31
	v_cvt_pk_bf16_f32 v74, v64, v65
	v_cvt_pk_bf16_f32 v68, v68, v69
	v_cvt_pk_bf16_f32 v69, v70, v71
	v_cvt_pk_bf16_f32 v70, v197, v232
	v_cvt_pk_bf16_f32 v71, v233, v234
	v_cvt_pk_bf16_f32 v64, v235, v236
	s_waitcnt lgkmcnt(0)
	v_mfma_f32_32x32x16_bf16 v[16:31], v[4:7], v[0:3], 0
	ds_read_b64_tr_b16 v[4:5], v211 offset:192
	ds_read_b64_tr_b16 v[6:7], v211 offset:2752
	ds_read_b64_tr_b16 v[232:233], v211 offset:5120
	ds_read_b64_tr_b16 v[234:235], v211 offset:7680
	v_cvt_pk_bf16_f32 v180, v12, v13
	v_cvt_pk_bf16_f32 v181, v14, v15
	v_cvt_pk_bf16_f32 v75, v66, v67
	v_cvt_pk_bf16_f32 v65, v237, v238
	v_cvt_pk_bf16_f32 v66, v239, v240
	s_waitcnt lgkmcnt(0)
	v_mfma_f32_32x32x16_bf16 v[48:63], v[232:235], v[180:183], v[48:63]
	ds_read_b64_tr_b16 v[232:233], v211 offset:5184
	ds_read_b64_tr_b16 v[234:235], v211 offset:7744
	v_cvt_pk_bf16_f32 v67, v241, v242
	v_add_f32_e32 v197, v243, v244
	s_lshl_b32 s0, s93, 7
	s_waitcnt lgkmcnt(0)
	v_mfma_f32_32x32x16_bf16 v[32:47], v[232:235], v[180:183], v[32:47]
	ds_read_b64_tr_b16 v[232:233], v211 offset:5248
	ds_read_b64_tr_b16 v[234:235], v211 offset:7808
	v_mfma_f32_32x32x16_bf16 v[0:15], v[4:7], v[0:3], 0
	s_waitcnt lgkmcnt(0)
	v_mfma_f32_32x32x16_bf16 v[16:31], v[232:235], v[180:183], v[16:31]
	ds_read_b64_tr_b16 v[232:233], v211 offset:5312
	ds_read_b64_tr_b16 v[234:235], v211 offset:7872
	s_waitcnt lgkmcnt(0)
	v_mfma_f32_32x32x16_bf16 v[0:15], v[232:235], v[180:183], v[0:15]
	ds_read_b64_tr_b16 v[180:181], v211 offset:10240
	ds_read_b64_tr_b16 v[182:183], v211 offset:12800
	ds_read_b64_tr_b16 v[232:233], v211 offset:10304
	ds_read_b64_tr_b16 v[234:235], v211 offset:12864
	s_waitcnt lgkmcnt(2)
	v_mfma_f32_32x32x16_bf16 v[48:63], v[180:183], v[176:179], v[48:63]
	ds_read_b64_tr_b16 v[180:181], v211 offset:10368
	ds_read_b64_tr_b16 v[182:183], v211 offset:12928
	s_waitcnt lgkmcnt(2)
	v_mfma_f32_32x32x16_bf16 v[32:47], v[232:235], v[176:179], v[32:47]
	ds_read_b64_tr_b16 v[232:233], v211 offset:10432
	ds_read_b64_tr_b16 v[234:235], v211 offset:12992
	s_waitcnt lgkmcnt(2)
	v_mfma_f32_32x32x16_bf16 v[16:31], v[180:183], v[176:179], v[16:31]
	ds_read_b64_tr_b16 v[180:181], v211 offset:15360
	ds_read_b64_tr_b16 v[182:183], v211 offset:17920
	s_waitcnt lgkmcnt(2)
	v_mfma_f32_32x32x16_bf16 v[0:15], v[232:235], v[176:179], v[0:15]
	ds_read_b64_tr_b16 v[232:233], v211 offset:15424
	ds_read_b64_tr_b16 v[234:235], v211 offset:17984
	ds_read_b64_tr_b16 v[176:177], v211 offset:15488
	ds_read_b64_tr_b16 v[178:179], v211 offset:18048
	s_waitcnt lgkmcnt(4)
	v_mfma_f32_32x32x16_bf16 v[48:63], v[180:183], v[172:175], v[48:63]
	ds_read_b64_tr_b16 v[180:181], v211 offset:15552
	ds_read_b64_tr_b16 v[182:183], v211 offset:18112
	s_waitcnt lgkmcnt(4)
	v_mfma_f32_32x32x16_bf16 v[32:47], v[232:235], v[172:175], v[32:47]
	ds_read_b64_tr_b16 v[232:233], v211 offset:20480
	ds_read_b64_tr_b16 v[234:235], v211 offset:23040
	s_waitcnt lgkmcnt(4)
	v_mfma_f32_32x32x16_bf16 v[16:31], v[176:179], v[172:175], v[16:31]
	ds_read_b64_tr_b16 v[176:177], v211 offset:20544
	ds_read_b64_tr_b16 v[178:179], v211 offset:23104
	s_waitcnt lgkmcnt(4)
	v_mfma_f32_32x32x16_bf16 v[0:15], v[180:183], v[172:175], v[0:15]
	ds_read_b64_tr_b16 v[180:181], v211 offset:20608
	ds_read_b64_tr_b16 v[182:183], v211 offset:23168
	ds_read_b64_tr_b16 v[172:173], v211 offset:20672
	ds_read_b64_tr_b16 v[174:175], v211 offset:23232
	s_waitcnt lgkmcnt(6)
	v_mfma_f32_32x32x16_bf16 v[48:63], v[232:235], v[168:171], v[48:63]
	ds_read_b64_tr_b16 v[232:233], v211 offset:25600
	ds_read_b64_tr_b16 v[234:235], v211 offset:28160
	s_waitcnt lgkmcnt(6)
	v_mfma_f32_32x32x16_bf16 v[32:47], v[176:179], v[168:171], v[32:47]
	ds_read_b64_tr_b16 v[176:177], v211 offset:25664
	ds_read_b64_tr_b16 v[178:179], v211 offset:28224
	s_waitcnt lgkmcnt(6)
	v_mfma_f32_32x32x16_bf16 v[16:31], v[180:183], v[168:171], v[16:31]
	ds_read_b64_tr_b16 v[180:181], v211 offset:25728
	ds_read_b64_tr_b16 v[182:183], v211 offset:28288
	s_waitcnt lgkmcnt(6)
	v_mfma_f32_32x32x16_bf16 v[0:15], v[172:175], v[168:171], v[0:15]
	ds_read_b64_tr_b16 v[172:173], v211 offset:25792
	ds_read_b64_tr_b16 v[174:175], v211 offset:28352
	ds_read_b64_tr_b16 v[168:169], v211 offset:30720
	ds_read_b64_tr_b16 v[170:171], v211 offset:33280
	s_waitcnt lgkmcnt(8)
; __device__ __forceinline__ s16x4 vtr(const LAS unsigned char* p) { return __builtin_bit_cast(s16x4, __builtin_amdgcn_ds_read_tr16_b64_v4i16((LAS v4i16_t*)p)); }
; __device__ __forceinline__ void attn_phase(LAS unsigned char* lds, const bf16* __restrict__ Q, const bf16* __restrict__ Kb, const bf16* __restrict__ Vb, unsigned char* ws, float* PM, int tid, int wave, int lane) {
;     ...
; #pragma unroll
;         for (int i = 0; i < 5; ++i)
; #pragma unroll
;             for (int s2 = 0; s2 < 2; ++s2)
; #pragma unroll
;                 for (int db = 0; db < 4; ++db) {
;                     const s16x4 lo = vtr(vbase + (32 * i + 16 * s2) * VROW + db * 64), hi = vtr(vbase + (32 * i + 16 * s2 + 8) * VROW + db * 64);
;                     const bf16x8 av = {lo[0], lo[1], lo[2], lo[3], hi[0], hi[1], hi[2], hi[3]};
;                     oacc[db] = __builtin_amdgcn_mfma_f32_32x32x16_bf16(av, __builtin_bit_cast(bf16x8, pw[i][s2]), oacc[db], 0, 0, 0);
;                 }
	v_mfma_f32_32x32x16_bf16 v[48:63], v[232:235], v[164:167], v[48:63]
	ds_read_b64_tr_b16 v[232:233], v211 offset:30784
	ds_read_b64_tr_b16 v[234:235], v211 offset:33344
	s_waitcnt lgkmcnt(8)
	v_mfma_f32_32x32x16_bf16 v[32:47], v[176:179], v[164:167], v[32:47]
	ds_read_b64_tr_b16 v[176:177], v211 offset:30848
	ds_read_b64_tr_b16 v[178:179], v211 offset:33408
	s_waitcnt lgkmcnt(8)
	v_mfma_f32_32x32x16_bf16 v[16:31], v[180:183], v[164:167], v[16:31]
	ds_read_b64_tr_b16 v[180:181], v211 offset:30912
	ds_read_b64_tr_b16 v[182:183], v211 offset:33472
	s_waitcnt lgkmcnt(8)
	v_mfma_f32_32x32x16_bf16 v[0:15], v[172:175], v[164:167], v[0:15]
	ds_read_b64_tr_b16 v[172:173], v211 offset:35840
	ds_read_b64_tr_b16 v[174:175], v211 offset:38400
	ds_read_b64_tr_b16 v[164:165], v211 offset:35904
	ds_read_b64_tr_b16 v[166:167], v211 offset:38464
	s_waitcnt lgkmcnt(10)
	v_mfma_f32_32x32x16_bf16 v[48:63], v[168:171], v[76:79], v[48:63]
	ds_read_b64_tr_b16 v[168:169], v211 offset:35968
	ds_read_b64_tr_b16 v[170:171], v211 offset:38528
	s_waitcnt lgkmcnt(10)
	v_mfma_f32_32x32x16_bf16 v[32:47], v[232:235], v[76:79], v[32:47]
	ds_read_b64_tr_b16 v[232:233], v211 offset:36032
	ds_read_b64_tr_b16 v[234:235], v211 offset:38592
	s_waitcnt lgkmcnt(10)
	v_mfma_f32_32x32x16_bf16 v[16:31], v[176:179], v[76:79], v[16:31]
	ds_read_b64_tr_b16 v[176:177], v211 offset:40960
	ds_read_b64_tr_b16 v[178:179], v211 offset:43520
	s_waitcnt lgkmcnt(10)
	v_mfma_f32_32x32x16_bf16 v[0:15], v[180:183], v[76:79], v[0:15]
	ds_read_b64_tr_b16 v[180:181], v211 offset:41024
	ds_read_b64_tr_b16 v[182:183], v211 offset:43584
	s_waitcnt lgkmcnt(10)
	v_mfma_f32_32x32x16_bf16 v[48:63], v[172:175], v[72:75], v[48:63]
	ds_read_b64_tr_b16 v[76:77], v211 offset:41088
	ds_read_b64_tr_b16 v[78:79], v211 offset:43648
	s_waitcnt lgkmcnt(10)
	v_mfma_f32_32x32x16_bf16 v[32:47], v[164:167], v[72:75], v[32:47]
	ds_read_b64_tr_b16 v[172:173], v211 offset:41152
	ds_read_b64_tr_b16 v[174:175], v211 offset:43712
	s_waitcnt lgkmcnt(10)
	v_mfma_f32_32x32x16_bf16 v[16:31], v[168:171], v[72:75], v[16:31]
	ds_read_b64_tr_b16 v[164:165], v211 offset:46080
	ds_read_b64_tr_b16 v[166:167], v211 offset:48640
	s_waitcnt lgkmcnt(10)
	v_mfma_f32_32x32x16_bf16 v[0:15], v[232:235], v[72:75], v[0:15]
	ds_read_b64_tr_b16 v[168:169], v211 offset:46144
	ds_read_b64_tr_b16 v[170:171], v211 offset:48704
	s_waitcnt lgkmcnt(10)
	v_mfma_f32_32x32x16_bf16 v[48:63], v[176:179], v[68:71], v[48:63]
	ds_read_b64_tr_b16 v[232:233], v211 offset:46208
	ds_read_b64_tr_b16 v[234:235], v211 offset:48768
	s_waitcnt lgkmcnt(10)
	v_mfma_f32_32x32x16_bf16 v[32:47], v[180:183], v[68:71], v[32:47]
	ds_read_b64_tr_b16 v[72:73], v211 offset:46272
	ds_read_b64_tr_b16 v[74:75], v211 offset:48832
	s_waitcnt lgkmcnt(10)
	v_mfma_f32_32x32x16_bf16 v[16:31], v[76:79], v[68:71], v[16:31]
	s_waitcnt lgkmcnt(8)
	v_mfma_f32_32x32x16_bf16 v[0:15], v[172:175], v[68:71], v[0:15]
	s_waitcnt lgkmcnt(6)
	v_mfma_f32_32x32x16_bf16 v[48:63], v[164:167], v[64:67], v[48:63]
	s_waitcnt lgkmcnt(4)
	v_mfma_f32_32x32x16_bf16 v[32:47], v[168:171], v[64:67], v[32:47]
	s_waitcnt lgkmcnt(2)
	v_mfma_f32_32x32x16_bf16 v[16:31], v[232:235], v[64:67], v[16:31]
	s_waitcnt lgkmcnt(0)
; __device__ __forceinline__ unsigned pk2(float lo, float hi) { f32x2_t v = {lo, hi}; bf16x2_t b = __builtin_convertvector(v, bf16x2_t); return __builtin_bit_cast(unsigned, b); }
; __device__ __forceinline__ void attn_phase(LAS unsigned char* lds, const bf16* __restrict__ Q, const bf16* __restrict__ Kb, const bf16* __restrict__ Vb, unsigned char* ws, float* PM, int tid, int wave, int lane) {
;     ...
;         const float inv = 1.f / l;
;         const size_t qpos = (size_t)(C.lq0 + 32 * wave + r) * C.d + C.res;
;     ...
; #pragma unroll
;         for (int db = 0; db < 4; ++db)
; #pragma unroll
;             for (int ep = 0; ep < 2; ++ep) {
;                 const int e0 = 2 * ep, e1 = 2 * ep + 1;
;                 unsigned ax = pk2(oacc[db][4 * e0] * inv, oacc[db][4 * e0 + 1] * inv), ay = pk2(oacc[db][4 * e0 + 2] * inv, oacc[db][4 * e0 + 3] * inv);
;                 unsigned bx = pk2(oacc[db][4 * e1] * inv, oacc[db][4 * e1 + 1] * inv), by = pk2(oacc[db][4 * e1 + 2] * inv, oacc[db][4 * e1 + 3] * inv);
;                 { auto rx = __builtin_amdgcn_permlane32_swap(ax, bx, false, false); ax = rx[0]; bx = rx[1]; }
;                 { auto ry = __builtin_amdgcn_permlane32_swap(ay, by, false, false); ay = ry[0]; by = ry[1]; }
;                 u32x4 o = {ax, ay, bx, by};
;                 *(u32x4*)(po + 16 * (4 * db + e0)) = o;
;             }
	v_mfma_f32_32x32x16_bf16 v[0:15], v[72:75], v[64:67], v[0:15]
	v_div_scale_f32 v64, s[8:9], v197, v197, 1.0
	v_rcp_f32_e32 v65, v64
	s_nop 0
	v_fma_f32 v66, -v64, v65, 1.0
	v_fmac_f32_e32 v65, v66, v65
	v_div_scale_f32 v66, vcc, 1.0, v197, 1.0
	v_mul_f32_e32 v67, v66, v65
	v_fma_f32 v68, -v64, v67, v66
	v_fmac_f32_e32 v67, v68, v65
	v_fma_f32 v64, -v64, v67, v66
	v_div_fmas_f32 v64, v64, v65, v67
	v_div_fixup_f32 v66, v64, v197, 1.0
	v_add_u32_e32 v67, s85, v210
	v_mov_b64_e32 v[64:65], s[96:97]
	v_mad_u64_u32 v[64:65], s[8:9], v67, s3, v[64:65]
	v_ashrrev_i32_e32 v69, 31, v67
	v_mov_b32_e32 v68, v65
	v_mad_u64_u32 v[68:69], s[8:9], v69, s3, v[68:69]
	s_ashr_i32 s85, s84, 31
	s_lshl_b64 s[8:9], s[84:85], 25
	s_add_u32 s1, s8, 0x1b400000
	s_addc_u32 s3, s9, 0
	s_cmp_lt_i32 s84, 2
	s_cselect_b32 s1, s1, 0x12c00000
	v_mov_b32_e32 v65, v68
	s_cselect_b32 s3, s3, 0
	s_add_u32 s8, s88, s1
	s_addc_u32 s9, s89, s3
	v_readlane_b32 s1, v245, 15
	v_readlane_b32 s3, v245, 16
	s_cmp_lt_i32 s84, 2
	s_cselect_b32 s8, s8, s1
	s_cselect_b32 s9, s9, s3
	v_lshlrev_b64 v[68:69], 11, v[64:65]
	v_pk_mul_f32 v[48:49], v[66:67], v[48:49] op_sel_hi:[0,1]
	v_pk_mul_f32 v[50:51], v[66:67], v[50:51] op_sel_hi:[0,1]
	v_pk_mul_f32 v[32:33], v[66:67], v[32:33] op_sel_hi:[0,1]
	v_pk_mul_f32 v[34:35], v[66:67], v[34:35] op_sel_hi:[0,1]
	v_pk_mul_f32 v[16:17], v[66:67], v[16:17] op_sel_hi:[0,1]
	v_pk_mul_f32 v[18:19], v[66:67], v[18:19] op_sel_hi:[0,1]
	v_pk_mul_f32 v[0:1], v[66:67], v[0:1] op_sel_hi:[0,1]
	v_pk_mul_f32 v[2:3], v[66:67], v[2:3] op_sel_hi:[0,1]
	v_lshl_add_u64 v[68:69], s[8:9], 0, v[68:69]
	s_lshl_b32 s96, s0, 1
	v_cvt_pk_bf16_f32 v48, v48, v49
	v_cvt_pk_bf16_f32 v49, v50, v51
	v_pk_mul_f32 v[50:51], v[66:67], v[52:53] op_sel_hi:[0,1]
	v_pk_mul_f32 v[52:53], v[66:67], v[54:55] op_sel_hi:[0,1]
	v_cvt_pk_bf16_f32 v32, v32, v33
	v_cvt_pk_bf16_f32 v33, v34, v35
	v_pk_mul_f32 v[34:35], v[66:67], v[36:37] op_sel_hi:[0,1]
	v_pk_mul_f32 v[36:37], v[66:67], v[38:39] op_sel_hi:[0,1]
	v_cvt_pk_bf16_f32 v16, v16, v17
	v_cvt_pk_bf16_f32 v17, v18, v19
	v_pk_mul_f32 v[18:19], v[66:67], v[20:21] op_sel_hi:[0,1]
	v_pk_mul_f32 v[20:21], v[66:67], v[22:23] op_sel_hi:[0,1]
	v_cvt_pk_bf16_f32 v0, v0, v1
	v_cvt_pk_bf16_f32 v1, v2, v3
	v_pk_mul_f32 v[2:3], v[66:67], v[4:5] op_sel_hi:[0,1]
	v_pk_mul_f32 v[4:5], v[66:67], v[6:7] op_sel_hi:[0,1]
	v_lshl_add_u64 v[68:69], v[68:69], 0, s[96:97]
	v_cvt_pk_bf16_f32 v50, v50, v51
	v_cvt_pk_bf16_f32 v51, v52, v53
	v_cvt_pk_bf16_f32 v34, v34, v35
	v_cvt_pk_bf16_f32 v35, v36, v37
	v_cvt_pk_bf16_f32 v18, v18, v19
	v_cvt_pk_bf16_f32 v19, v20, v21
	v_cvt_pk_bf16_f32 v2, v2, v3
	v_cvt_pk_bf16_f32 v3, v4, v5
	v_lshl_add_u64 v[68:69], v[68:69], 0, v[192:193]
	v_permlane32_swap_b32_e32 v48, v50
	v_permlane32_swap_b32_e32 v49, v51
	v_permlane32_swap_b32_e32 v32, v34
	v_permlane32_swap_b32_e32 v33, v35
	v_permlane32_swap_b32_e32 v16, v18
	v_permlane32_swap_b32_e32 v17, v19
	v_permlane32_swap_b32_e32 v0, v2
	v_permlane32_swap_b32_e32 v1, v3
	global_store_dwordx4 v[68:69], v[48:51], off
	global_store_dwordx4 v[68:69], v[32:35], off offset:64
	global_store_dwordx4 v[68:69], v[16:19], off offset:128
	v_pk_mul_f32 v[48:49], v[66:67], v[56:57] op_sel_hi:[0,1]
	v_pk_mul_f32 v[50:51], v[66:67], v[58:59] op_sel_hi:[0,1]
	v_pk_mul_f32 v[32:33], v[66:67], v[40:41] op_sel_hi:[0,1]
	v_pk_mul_f32 v[34:35], v[66:67], v[42:43] op_sel_hi:[0,1]
	v_pk_mul_f32 v[16:17], v[66:67], v[24:25] op_sel_hi:[0,1]
	v_pk_mul_f32 v[18:19], v[66:67], v[26:27] op_sel_hi:[0,1]
	global_store_dwordx4 v[68:69], v[0:3], off offset:192
	v_cvt_pk_bf16_f32 v48, v48, v49
	v_cvt_pk_bf16_f32 v49, v50, v51
	v_pk_mul_f32 v[0:1], v[66:67], v[8:9] op_sel_hi:[0,1]
	v_pk_mul_f32 v[2:3], v[66:67], v[10:11] op_sel_hi:[0,1]
	v_pk_mul_f32 v[50:51], v[66:67], v[60:61] op_sel_hi:[0,1]
	v_pk_mul_f32 v[52:53], v[66:67], v[62:63] op_sel_hi:[0,1]
	v_cvt_pk_bf16_f32 v32, v32, v33
	v_cvt_pk_bf16_f32 v33, v34, v35
	v_pk_mul_f32 v[34:35], v[66:67], v[44:45] op_sel_hi:[0,1]
	v_pk_mul_f32 v[36:37], v[66:67], v[46:47] op_sel_hi:[0,1]
	v_cvt_pk_bf16_f32 v16, v16, v17
	v_cvt_pk_bf16_f32 v17, v18, v19
	v_pk_mul_f32 v[18:19], v[66:67], v[28:29] op_sel_hi:[0,1]
	v_pk_mul_f32 v[20:21], v[66:67], v[30:31] op_sel_hi:[0,1]
	v_cvt_pk_bf16_f32 v0, v0, v1
	v_cvt_pk_bf16_f32 v1, v2, v3
	v_pk_mul_f32 v[2:3], v[66:67], v[12:13] op_sel_hi:[0,1]
	v_pk_mul_f32 v[4:5], v[66:67], v[14:15] op_sel_hi:[0,1]
	v_cvt_pk_bf16_f32 v50, v50, v51
	v_cvt_pk_bf16_f32 v51, v52, v53
	v_cvt_pk_bf16_f32 v34, v34, v35
	v_cvt_pk_bf16_f32 v35, v36, v37
	v_cvt_pk_bf16_f32 v18, v18, v19
	v_cvt_pk_bf16_f32 v19, v20, v21
	v_cvt_pk_bf16_f32 v2, v2, v3
	v_cvt_pk_bf16_f32 v3, v4, v5
	v_permlane32_swap_b32_e32 v48, v50
	v_permlane32_swap_b32_e32 v49, v51
	v_permlane32_swap_b32_e32 v32, v34
	v_permlane32_swap_b32_e32 v33, v35
	v_permlane32_swap_b32_e32 v16, v18
	v_permlane32_swap_b32_e32 v17, v19
	v_permlane32_swap_b32_e32 v0, v2
	v_permlane32_swap_b32_e32 v1, v3
	global_store_dwordx4 v[68:69], v[48:51], off offset:32
	global_store_dwordx4 v[68:69], v[32:35], off offset:96
	global_store_dwordx4 v[68:69], v[16:19], off offset:160
	global_store_dwordx4 v[68:69], v[0:3], off offset:224
	s_mov_b64 s[0:1], exec
	v_readlane_b32 s8, v245, 46
	v_readlane_b32 s9, v245, 47
	s_and_b64 s[8:9], s[0:1], s[8:9]
	s_mov_b64 exec, s[8:9]
	s_cbranch_execz .LBB0_573
	s_lshl_b64 s[8:9], s[84:85], 17
	v_lshl_add_u64 v[0:1], v[64:65], 3, s[8:9]
	v_readlane_b32 s8, v245, 38
	v_or_b32_e32 v0, s93, v0
	v_readlane_b32 s9, v245, 39
	s_nop 1
	v_lshl_add_u64 v[0:1], v[0:1], 3, s[8:9]
	global_store_dwordx2 v[0:1], v[196:197], off
	s_branch .LBB0_573

; __device__ __forceinline__ bf16* po_base(unsigned char* ws, int pat) { return (bf16*)(ws + (pat < 2 ? 436 * MiB + (size_t)pat * 32 * MiB : WS_Y)); }
; __device__ __forceinline__ void attn_combine(unsigned char* ws, const float* __restrict__ PM, bf16* CAT, int gtid, int gthreads, int iend = S * 128) {
;     for (int idx = gtid; idx < iend; idx += gthreads) {
;         const int t = idx >> 7, c = (idx & 127) * 8, hh = c >> 7;
;         float mm[3], ll[3];
; #pragma unroll
;         for (int p = 0; p < 3; ++p) { const f32x2_t ml = *(const f32x2_t*)(PM + (((size_t)p * S + t) * 8 + hh) * 2); mm[p] = ml[0]; ll[p] = ml[1]; }
;         const float ma = fmaxf(mm[0], fmaxf(mm[1], mm[2]));
;         float w[3], den = 0.f;
; #pragma unroll
;         for (int p = 0; p < 3; ++p) { w[p] = exp2f(mm[p] - ma) * ll[p]; den += w[p]; }
;         const float inv = 1.f / den;
;         float o[8] = {0.f, 0.f, 0.f, 0.f, 0.f, 0.f, 0.f, 0.f};
; #pragma unroll
;         for (int p = 0; p < 3; ++p) {
;             const u32x4 v = *(const u32x4*)(po_base(ws, p) + (size_t)t * 1024 + c); const float wp = w[p] * inv;
; __global__ void __launch_bounds__(512, 2) mega(Args a) {
;     ...
;             const long NIT = (long)S * 128, W = 192 * 5 + 64 * 3;
;             const long c0 = b <= NG ? 3L * b : 192L + 5L * (b - NG), c1 = (b + 1) <= NG ? 3L * (b + 1) : 192L + 5L * (b + 1 - NG);
;             const int i0 = (int)(NIT * c0 / W), i1 = (int)(NIT * c1 / W);
;             attn_combine(ws, PM, CAT, i0 + tid, 512, i1);
.LBB0_790:
	s_lshl_b64 s[4:5], s[0:1], 21
	s_lshr_b64 s[0:1], s[0:1], 11
	s_mul_hi_u32 s6, s4, 0xe38e38e
	s_mul_i32 s7, s4, 0xe38e38e
	s_mul_i32 s8, s0, 0x38e38e39
	s_mul_hi_u32 s4, s4, 0x38e38e39
	s_mul_hi_u32 s1, s0, 0x38e38e39
	s_add_u32 s4, s8, s4
	s_addc_u32 s1, s1, 0
	s_add_u32 s4, s7, s4
	s_addc_u32 s4, s6, 0
	s_add_u32 s1, s1, s4
	s_addc_u32 s4, 0, 0
	s_mul_hi_u32 s6, s0, 0xe38e38e
	s_mul_i32 s0, s0, 0xe38e38e
	s_add_u32 s0, s0, s1
	s_addc_u32 s1, s6, s4
	s_ashr_i32 s4, s5, 31
	s_mul_i32 s5, s4, 0xe38e38e
	s_mul_hi_u32 s6, s4, 0x38e38e39
	s_add_i32 s5, s6, s5
	s_mul_i32 s4, s4, 0x38e38e39
	s_add_i32 s5, s5, s4
	s_add_u32 s0, s0, s4
	s_addc_u32 s1, s1, s5
	s_lshr_b32 s4, s1, 31
	s_lshr_b64 s[0:1], s[0:1], 6
	s_add_i32 s4, s0, s4
	s_lshl_b64 s[0:1], s[2:3], 21
	s_lshr_b64 s[2:3], s[2:3], 11
	s_mul_hi_u32 s5, s0, 0xe38e38e
	s_mul_i32 s6, s0, 0xe38e38e
	s_mul_i32 s7, s2, 0x38e38e39
	s_mul_hi_u32 s0, s0, 0x38e38e39
	s_mul_hi_u32 s3, s2, 0x38e38e39
	s_add_u32 s0, s7, s0
	s_addc_u32 s3, s3, 0
	s_add_u32 s0, s6, s0
	s_addc_u32 s0, s5, 0
	s_add_u32 s0, s3, s0
	s_addc_u32 s3, 0, 0
	s_mul_hi_u32 s5, s2, 0xe38e38e
	s_mul_i32 s2, s2, 0xe38e38e
	s_add_u32 s0, s2, s0
	s_addc_u32 s2, s5, s3
	s_ashr_i32 s1, s1, 31
	s_mul_i32 s3, s1, 0xe38e38e
	s_mul_hi_u32 s5, s1, 0x38e38e39
	s_add_i32 s3, s5, s3
	s_mul_i32 s1, s1, 0x38e38e39
	s_add_i32 s3, s3, s1
	s_add_u32 s0, s0, s1
	s_addc_u32 s1, s2, s3
	s_lshr_b32 s2, s1, 31
	s_lshr_b64 s[0:1], s[0:1], 6
	s_add_i32 s18, s0, s2
	s_mov_b64 s[2:3], exec
	s_cmp_lt_i32 s66, 64
	s_cbranch_scc1 .Lcmb_small
	s_sub_i32 s4, s66, 64
	s_mul_i32 s4, s4, 0x2800
	s_add_i32 s4, s4, 0x20000
	s_add_i32 s18, s4, 0x2800
	s_branch .Lcmb_split
.Lcmb_small:
	s_lshl_b32 s4, s66, 11
	s_add_i32 s18, s4, 0x800
.Lcmb_split:
	v_add_u32_e32 v2, s4, v186
	v_readlane_b32 s26, v245, 38
	v_readlane_b32 s27, v245, 39
	s_add_u32 s6, s88, 0x600000
	s_addc_u32 s7, s89, 0
	s_add_u32 s8, s88, 0x700000
	s_addc_u32 s9, s89, 0
	s_add_u32 s16, s88, 0x1b400000
	s_addc_u32 s17, s89, 0
	s_add_u32 s20, s88, 0x1d400000
	s_addc_u32 s21, s89, 0
	v_readlane_b32 s22, v245, 15
	v_readlane_b32 s23, v245, 16
	s_sub_i32 s0, s18, s4
	s_add_i32 s0, s0, 2047
	s_lshr_b32 s0, s0, 11
	s_add_i32 s1, s18, -1
	s_mov_b32 s19, 0xc2fc0000
	v_mov_b32_e32 v1, 0
	v_mov_b32_e32 v4, 0x42800000
	v_not_b32_e32 v5, 63
	v_min_i32_e32 v60, s1, v2
	v_ashrrev_i32_e32 v59, 7, v60
	v_lshrrev_b32_e32 v61, 1, v60
	v_and_b32_e32 v61, 56, v61
	v_lshl_or_b32 v61, v59, 6, v61
	global_load_dwordx2 v[40:41], v61, s[26:27]
	global_load_dwordx2 v[42:43], v61, s[6:7]
	global_load_dwordx2 v[44:45], v61, s[8:9]
	v_and_b32_e32 v58, 0x7f, v60
	v_lshlrev_b32_e32 v60, 4, v60
	v_lshlrev_b32_e32 v58, 4, v58
	global_load_dwordx4 v[46:49], v60, s[16:17]
	v_lshl_or_b32 v58, v59, 12, v58
	global_load_dwordx4 v[50:53], v60, s[20:21]
	global_load_dwordx4 v[54:57], v60, s[22:23]
	v_add_u32_e32 v84, 512, v2
	v_min_i32_e32 v84, s1, v84
	v_ashrrev_i32_e32 v83, 7, v84
	v_lshrrev_b32_e32 v85, 1, v84
	v_and_b32_e32 v85, 56, v85
	v_lshl_or_b32 v85, v83, 6, v85
	global_load_dwordx2 v[64:65], v85, s[26:27]
	global_load_dwordx2 v[66:67], v85, s[6:7]
	global_load_dwordx2 v[68:69], v85, s[8:9]
	v_and_b32_e32 v82, 0x7f, v84
	v_lshlrev_b32_e32 v84, 4, v84
	v_lshlrev_b32_e32 v82, 4, v82
	global_load_dwordx4 v[70:73], v84, s[16:17]
	v_lshl_or_b32 v82, v83, 12, v82
	global_load_dwordx4 v[74:77], v84, s[20:21]
	global_load_dwordx4 v[78:81], v84, s[22:23]
	v_add_u32_e32 v108, 1024, v2
	v_min_i32_e32 v108, s1, v108
	v_ashrrev_i32_e32 v107, 7, v108
	v_lshrrev_b32_e32 v109, 1, v108
	v_and_b32_e32 v109, 56, v109
	v_lshl_or_b32 v109, v107, 6, v109
	global_load_dwordx2 v[88:89], v109, s[26:27]
	global_load_dwordx2 v[90:91], v109, s[6:7]
	global_load_dwordx2 v[92:93], v109, s[8:9]
	v_and_b32_e32 v106, 0x7f, v108
	v_lshlrev_b32_e32 v108, 4, v108
	v_lshlrev_b32_e32 v106, 4, v106
	global_load_dwordx4 v[94:97], v108, s[16:17]
	v_lshl_or_b32 v106, v107, 12, v106
	global_load_dwordx4 v[98:101], v108, s[20:21]
	global_load_dwordx4 v[102:105], v108, s[22:23]
	v_add_u32_e32 v132, 1536, v2
	v_min_i32_e32 v132, s1, v132
	v_ashrrev_i32_e32 v131, 7, v132
	v_lshrrev_b32_e32 v133, 1, v132
	v_and_b32_e32 v133, 56, v133
	v_lshl_or_b32 v133, v131, 6, v133
	global_load_dwordx2 v[112:113], v133, s[26:27]
	global_load_dwordx2 v[114:115], v133, s[6:7]
	global_load_dwordx2 v[116:117], v133, s[8:9]
	v_and_b32_e32 v130, 0x7f, v132
	v_lshlrev_b32_e32 v132, 4, v132
	v_lshlrev_b32_e32 v130, 4, v130
	global_load_dwordx4 v[118:121], v132, s[16:17]
	v_lshl_or_b32 v130, v131, 12, v130
	global_load_dwordx4 v[122:125], v132, s[20:21]
	global_load_dwordx4 v[126:129], v132, s[22:23]
	v_add_u32_e32 v2, 2048, v2
